# adds: attention merge (second dilation group) batches its LDS reads into dead K/V registers instead of read-wait-add-write per element
# speedup vs baseline: 1.0233x; 1.0003x over previous
; DI int crow(int r, int hi) { return (r & 3) + 8 * (r >> 2) + 4 * hi; }
; DI void attn_merge(LAS float* Ot, LAS float* Ls, bool first, int x, int hi, const f32x16& o0, const f32x16& o1, float lsum) {
;     lsum += __shfl_xor(lsum, 32);
;     const int cx = colx(x);
;     if (first) {
; #pragma unroll
;         for (int r = 0; r < 16; ++r) { Ot[crow(r, hi) * 512 + cx] = o0[r]; Ot[(32 + crow(r, hi)) * 512 + cx] = o1[r]; }
;         if (hi == 0) Ls[x] = lsum;
;     } else {
; #pragma unroll
;         for (int r = 0; r < 16; ++r) { Ot[crow(r, hi) * 512 + cx] += o0[r]; Ot[(32 + crow(r, hi)) * 512 + cx] += o1[r]; }
;         if (hi == 0) Ls[x] += lsum;
.LBB0_510:
	ds_bpermute_b32 v67, v218, v241
	s_waitcnt vmcnt(2)
	v_lshrrev_b32_e32 v68, 5, v226
	v_lshl_add_u32 v66, v1, 13, 0
	v_bitop3_b32 v68, v68, v226, 15 bitop3:0x6c
	v_lshl_add_u32 v68, v68, 2, v66
	v_cndmask_b32_e64 v69, 0, 1, s[84:85]
	s_waitcnt lgkmcnt(0)
	v_add_f32_e32 v67, v241, v67
	s_mov_b64 s[86:87], -1
	v_cmp_ne_u32_e64 s[20:21], 1, v69
	s_andn2_b64 vcc, exec, s[84:85]
	s_waitcnt vmcnt(15)
	v_add_u32_e32 v88, 0x10000, v68
	v_add_u32_e32 v86, 0x10800, v68
	v_add_u32_e32 v87, 0x11000, v68
	v_add_u32_e32 v80, 0x11800, v68
	v_add_u32_e32 v81, 0x14000, v68
	s_waitcnt vmcnt(0)
	v_add_u32_e32 v78, 0x14800, v68
	v_add_u32_e32 v79, 0x15000, v68
	v_add_u32_e32 v76, 0x15800, v68
	v_add_u32_e32 v77, 0x18000, v68
	v_add_u32_e32 v74, 0x18800, v68
	v_add_u32_e32 v75, 0x19000, v68
	v_add_u32_e32 v72, 0x19800, v68
	v_add_u32_e32 v73, 0x1c000, v68
	v_add_u32_e32 v70, 0x1c800, v68
	v_add_u32_e32 v71, 0x1d000, v68
	v_add_u32_e32 v69, 0x1d800, v68
	s_cbranch_vccnz .LBB0_514
	s_waitcnt vmcnt(14)
	v_cmp_gt_u32_e32 vcc, 32, v224
	ds_read_b32 v134, v88
	ds_read2st64_b32 v[118:119], v68 offset1:8
	ds_read_b32 v135, v86
	ds_read_b32 v136, v87
	ds_read2st64_b32 v[120:121], v68 offset0:16 offset1:24
	ds_read_b32 v137, v80
	ds_read_b32 v138, v81
	ds_read2st64_b32 v[122:123], v68 offset0:64 offset1:72
	ds_read_b32 v139, v78
	ds_read_b32 v140, v79
	ds_read2st64_b32 v[124:125], v68 offset0:80 offset1:88
	ds_read_b32 v141, v76
	s_waitcnt lgkmcnt(0)
	v_add_f32_e32 v134, v50, v134
	v_add_f32_e32 v118, v34, v118
	v_add_f32_e32 v119, v35, v119
	v_add_f32_e32 v135, v51, v135
	v_add_f32_e32 v136, v52, v136
	v_add_f32_e32 v120, v36, v120
	v_add_f32_e32 v121, v37, v121
	v_add_f32_e32 v137, v53, v137
	v_add_f32_e32 v138, v54, v138
	v_add_f32_e32 v122, v38, v122
	v_add_f32_e32 v123, v39, v123
	v_add_f32_e32 v139, v55, v139
	v_add_f32_e32 v140, v56, v140
	v_add_f32_e32 v124, v40, v124
	v_add_f32_e32 v125, v41, v125
	v_add_f32_e32 v141, v57, v141
	ds_write_b32 v88, v134
	ds_write2st64_b32 v68, v118, v119 offset1:8
	ds_write_b32 v86, v135
	ds_write_b32 v87, v136
	ds_write2st64_b32 v68, v120, v121 offset0:16 offset1:24
	ds_write_b32 v80, v137
	ds_write_b32 v81, v138
	ds_write2st64_b32 v68, v122, v123 offset0:64 offset1:72
	ds_write_b32 v78, v139
	ds_write_b32 v79, v140
	ds_write2st64_b32 v68, v124, v125 offset0:80 offset1:88
	ds_write_b32 v76, v141
	ds_read_b32 v142, v77
	ds_read2st64_b32 v[126:127], v68 offset0:128 offset1:136
	ds_read_b32 v143, v74
	ds_read_b32 v144, v75
	ds_read2st64_b32 v[128:129], v68 offset0:144 offset1:152
	ds_read_b32 v145, v72
	ds_read_b32 v146, v73
	ds_read2st64_b32 v[130:131], v68 offset0:192 offset1:200
	ds_read_b32 v147, v70
	ds_read_b32 v148, v71
	ds_read2st64_b32 v[132:133], v68 offset0:208 offset1:216
	ds_read_b32 v149, v69
	s_waitcnt lgkmcnt(0)
	v_add_f32_e32 v142, v58, v142
	v_add_f32_e32 v126, v42, v126
	v_add_f32_e32 v127, v43, v127
	v_add_f32_e32 v143, v59, v143
	v_add_f32_e32 v144, v60, v144
	v_add_f32_e32 v128, v44, v128
	v_add_f32_e32 v129, v45, v129
	v_add_f32_e32 v145, v61, v145
	v_add_f32_e32 v146, v62, v146
	v_add_f32_e32 v130, v46, v130
	v_add_f32_e32 v131, v47, v131
	v_add_f32_e32 v147, v63, v147
	v_add_f32_e32 v148, v64, v148
	v_add_f32_e32 v132, v48, v132
	v_add_f32_e32 v133, v49, v133
	v_add_f32_e32 v149, v65, v149
	ds_write_b32 v77, v142
	ds_write2st64_b32 v68, v126, v127 offset0:128 offset1:136
	ds_write_b32 v74, v143
	ds_write_b32 v75, v144
	ds_write2st64_b32 v68, v128, v129 offset0:144 offset1:152
	ds_write_b32 v72, v145
	ds_write_b32 v73, v146
	ds_write2st64_b32 v68, v130, v131 offset0:192 offset1:200
	ds_write_b32 v70, v147
	ds_write_b32 v71, v148
	ds_write2st64_b32 v68, v132, v133 offset0:208 offset1:216
	ds_write_b32 v69, v149
	s_and_saveexec_b64 s[84:85], vcc
	s_cbranch_execz .LBB0_513
	v_lshl_add_u32 v89, v226, 2, 0
	v_add_u32_e32 v89, 0x20000, v89
	ds_read_b32 v90, v89
	s_waitcnt lgkmcnt(0)
	v_add_f32_e32 v90, v67, v90
	ds_write_b32 v89, v90

; DI int crow(int r, int hi) { return (r & 3) + 8 * (r >> 2) + 4 * hi; }
; DI void attn_merge(LAS float* Ot, LAS float* Ls, bool first, int x, int hi, const f32x16& o0, const f32x16& o1, float lsum) {
;     lsum += __shfl_xor(lsum, 32);
;     const int cx = colx(x);
;     if (first) {
; #pragma unroll
;         for (int r = 0; r < 16; ++r) { Ot[crow(r, hi) * 512 + cx] = o0[r]; Ot[(32 + crow(r, hi)) * 512 + cx] = o1[r]; }
;         if (hi == 0) Ls[x] = lsum;
;     } else {
; #pragma unroll
;         for (int r = 0; r < 16; ++r) { Ot[crow(r, hi) * 512 + cx] += o0[r]; Ot[(32 + crow(r, hi)) * 512 + cx] += o1[r]; }
;         if (hi == 0) Ls[x] += lsum;
.LBB0_518:
	ds_bpermute_b32 v34, v218, v183
	v_lshrrev_b32_e32 v35, 5, v225
	v_bitop3_b32 v35, v35, v225, 15 bitop3:0x6c
	v_lshl_add_u32 v35, v35, 2, v66
	s_mov_b64 s[84:85], -1
	s_waitcnt lgkmcnt(0)
	v_add_f32_e32 v34, v183, v34
	s_and_b64 vcc, exec, s[20:21]
	v_add_u32_e32 v51, 0x10000, v35
	v_add_u32_e32 v49, 0x10800, v35
	v_add_u32_e32 v50, 0x11000, v35
	v_add_u32_e32 v47, 0x11800, v35
	v_add_u32_e32 v48, 0x14000, v35
	v_add_u32_e32 v45, 0x14800, v35
	v_add_u32_e32 v46, 0x15000, v35
	v_add_u32_e32 v43, 0x15800, v35
	v_add_u32_e32 v44, 0x18000, v35
	v_add_u32_e32 v41, 0x18800, v35
	v_add_u32_e32 v42, 0x19000, v35
	v_add_u32_e32 v39, 0x19800, v35
	v_add_u32_e32 v40, 0x1c000, v35
	v_add_u32_e32 v37, 0x1c800, v35
	v_add_u32_e32 v38, 0x1d000, v35
	v_add_u32_e32 v36, 0x1d800, v35
	s_cbranch_vccnz .LBB0_522
	v_cmp_gt_u32_e32 vcc, 32, v224
	ds_read2st64_b32 v[118:119], v35 offset1:8
	ds_read_b32 v134, v51
	ds_read_b32 v135, v49
	ds_read2st64_b32 v[120:121], v35 offset0:16 offset1:24
	ds_read_b32 v136, v50
	ds_read_b32 v137, v47
	ds_read2st64_b32 v[122:123], v35 offset0:64 offset1:72
	ds_read_b32 v138, v48
	ds_read_b32 v139, v45
	ds_read2st64_b32 v[124:125], v35 offset0:80 offset1:88
	ds_read_b32 v140, v46
	ds_read_b32 v141, v43
	s_waitcnt lgkmcnt(0)
	v_add_f32_e32 v118, v18, v118
	v_add_f32_e32 v119, v19, v119
	v_add_f32_e32 v134, v2, v134
	v_add_f32_e32 v135, v3, v135
	v_add_f32_e32 v120, v20, v120
	v_add_f32_e32 v121, v21, v121
	v_add_f32_e32 v136, v4, v136
	v_add_f32_e32 v137, v5, v137
	v_add_f32_e32 v122, v22, v122
	v_add_f32_e32 v123, v23, v123
	v_add_f32_e32 v138, v6, v138
	v_add_f32_e32 v139, v7, v139
	v_add_f32_e32 v124, v24, v124
	v_add_f32_e32 v125, v25, v125
	v_add_f32_e32 v140, v8, v140
	v_add_f32_e32 v141, v9, v141
	ds_write2st64_b32 v35, v118, v119 offset1:8
	ds_write_b32 v51, v134
	ds_write_b32 v49, v135
	ds_write2st64_b32 v35, v120, v121 offset0:16 offset1:24
	ds_write_b32 v50, v136
	ds_write_b32 v47, v137
	ds_write2st64_b32 v35, v122, v123 offset0:64 offset1:72
	ds_write_b32 v48, v138
	ds_write_b32 v45, v139
	ds_write2st64_b32 v35, v124, v125 offset0:80 offset1:88
	ds_write_b32 v46, v140
	ds_write_b32 v43, v141
	ds_read2st64_b32 v[126:127], v35 offset0:128 offset1:136
	ds_read_b32 v142, v44
	ds_read_b32 v143, v41
	ds_read2st64_b32 v[128:129], v35 offset0:144 offset1:152
	ds_read_b32 v144, v42
	ds_read_b32 v145, v39
	ds_read2st64_b32 v[130:131], v35 offset0:192 offset1:200
	ds_read_b32 v146, v40
	ds_read_b32 v147, v37
	ds_read2st64_b32 v[132:133], v35 offset0:208 offset1:216
	ds_read_b32 v148, v38
	ds_read_b32 v149, v36
	s_waitcnt lgkmcnt(0)
	v_add_f32_e32 v126, v26, v126
	v_add_f32_e32 v127, v27, v127
	v_add_f32_e32 v142, v10, v142
	v_add_f32_e32 v143, v11, v143
	v_add_f32_e32 v128, v28, v128
	v_add_f32_e32 v129, v29, v129
	v_add_f32_e32 v144, v12, v144
	v_add_f32_e32 v145, v13, v145
	v_add_f32_e32 v130, v30, v130
	v_add_f32_e32 v131, v31, v131
	v_add_f32_e32 v146, v14, v146
	v_add_f32_e32 v147, v15, v147
	v_add_f32_e32 v132, v32, v132
	v_add_f32_e32 v133, v33, v133
	v_add_f32_e32 v148, v16, v148
	v_add_f32_e32 v149, v17, v149
	ds_write2st64_b32 v35, v126, v127 offset0:128 offset1:136
	ds_write_b32 v44, v142
	ds_write_b32 v41, v143
	ds_write2st64_b32 v35, v128, v129 offset0:144 offset1:152
	ds_write_b32 v42, v144
	ds_write_b32 v39, v145
	ds_write2st64_b32 v35, v130, v131 offset0:192 offset1:200
	ds_write_b32 v40, v146
	ds_write_b32 v37, v147
	ds_write2st64_b32 v35, v132, v133 offset0:208 offset1:216
	ds_write_b32 v38, v148
	ds_write_b32 v36, v149
	s_and_saveexec_b64 s[20:21], vcc
	s_cbranch_execz .LBB0_521
	v_lshl_add_u32 v52, v225, 2, 0
	v_add_u32_e32 v52, 0x20000, v52
	ds_read_b32 v53, v52
	s_waitcnt lgkmcnt(0)
	v_add_f32_e32 v53, v34, v53
	ds_write_b32 v52, v53
